# LRU tile loop: all 16 local-scan LDS reads issued up front; the 16 re-scan reads issued right behind the tile barrier ahead of the carry chain
# speedup vs baseline: 1.0295x; 1.0029x over previous
.LBB0_932:
	s_waitcnt lgkmcnt(0)
	ds_read_b128 v[98:101], v170
	ds_read_b128 v[102:105], v170 offset:16
	ds_read_b128 v[166:169], v170 offset:128
	ds_read_b128 v[178:181], v170 offset:144
	ds_read2_b32 v[182:183], v109 offset1:16
	ds_read2_b32 v[226:227], v109 offset0:64 offset1:80
	ds_read2_b32 v[228:229], v109 offset0:128 offset1:144
	ds_read2_b32 v[230:231], v109 offset0:192 offset1:208
	ds_read2_b32 v[232:233], v109 offset0:32 offset1:48
	ds_read2_b32 v[234:235], v109 offset0:96 offset1:112
	ds_read2_b32 v[236:237], v109 offset0:160 offset1:176
	ds_read2_b32 v[238:239], v109 offset0:224 offset1:240
	s_waitcnt lgkmcnt(11)
	v_cvt_pk_bf16_f32 v162, v98, v99
	v_cvt_pk_bf16_f32 v163, v100, v101
	s_waitcnt lgkmcnt(10)
	v_cvt_pk_bf16_f32 v164, v102, v103
	v_cvt_pk_bf16_f32 v165, v104, v105
	s_waitcnt lgkmcnt(9)
	v_cvt_pk_bf16_f32 v166, v166, v167
	v_cvt_pk_bf16_f32 v167, v168, v169
	s_waitcnt lgkmcnt(8)
	v_cvt_pk_bf16_f32 v168, v178, v179
	v_cvt_pk_bf16_f32 v169, v180, v181
	v_mfma_f32_16x16x32_bf16 v[98:101], v[162:165], v[6:9], v[66:69]
	s_nop 0
	v_mfma_f32_16x16x32_bf16 v[178:181], v[166:169], v[2:5], v[98:101]
	v_mfma_f32_16x16x32_bf16 v[190:193], v[162:165], v[34:37], v[82:85]
	v_mfma_f32_16x16x32_bf16 v[190:193], v[166:169], v[38:41], v[190:193]
	s_nop 5
	v_mul_f32_e32 v98, 0xbfb8aa3b, v178
	v_exp_f32_e32 v98, v98
	v_mfma_f32_16x16x32_bf16 v[102:105], v[162:165], v[10:13], v[70:73]
	v_add_f32_e32 v98, 1.0, v98
	v_rcp_f32_e32 v98, v98
	v_mul_f32_e32 v99, 0xbfb8aa3b, v190
	v_exp_f32_e32 v99, v99
	v_mfma_f32_16x16x32_bf16 v[194:197], v[166:169], v[14:17], v[102:105]
	v_mul_f32_e32 v98, v121, v98
	v_exp_f32_e32 v145, v98
	v_add_f32_e32 v98, 1.0, v99
	v_mul_f32_e32 v102, 0xbfb8aa3b, v179
	v_rcp_f32_e32 v103, v98
	v_fma_f32 v104, -v145, v145, 1.0 clamp
	s_nop 0
	v_exp_f32_e32 v178, v102
	v_sqrt_f32_e32 v104, v104
	s_waitcnt lgkmcnt(0)
	v_mul_f32_e32 v102, v103, v182
	v_mul_f32_e32 v182, 0xbfb8aa3b, v191
	v_add_f32_e32 v178, 1.0, v178
	v_mul_f32_e32 v179, v104, v102
	v_mfma_f32_16x16x32_bf16 v[102:105], v[162:165], v[42:45], v[86:89]
	v_rcp_f32_e32 v178, v178
	v_exp_f32_e32 v182, v182
	v_mul_f32_e32 v190, 0xbfb8aa3b, v195
	v_mfma_f32_16x16x32_bf16 v[198:201], v[166:169], v[46:49], v[102:105]
	v_exp_f32_e32 v190, v190
	v_add_f32_e32 v182, 1.0, v182
	v_rcp_f32_e32 v182, v182
	s_nop 0
	v_mul_f32_e32 v102, v121, v178
	v_exp_f32_e32 v178, v102
	v_mfma_f32_16x16x32_bf16 v[102:105], v[162:165], v[50:53], v[94:97]
	v_fma_f32 v185, -v178, v178, 1.0 clamp
	v_mfma_f32_16x16x32_bf16 v[202:205], v[166:169], v[54:57], v[102:105]
	s_nop 0
	s_nop 4
	v_mul_f32_e32 v102, 0xbfb8aa3b, v180
	v_mfma_f32_16x16x32_bf16 v[186:189], v[162:165], v[18:21], v[74:77]
	v_exp_f32_e32 v180, v102
	v_mfma_f32_16x16x32_bf16 v[98:101], v[162:165], v[26:29], v[78:81]
	v_mfma_f32_16x16x32_bf16 v[102:105], v[162:165], v[58:61], v[90:93]
	v_sqrt_f32_e32 v164, v185
	v_add_f32_e32 v165, 1.0, v180
	v_mfma_f32_16x16x32_bf16 v[186:189], v[166:169], v[22:25], v[186:189]
	v_rcp_f32_e32 v165, v165
	s_nop 0
	v_mul_f32_e32 v162, v182, v226
	v_mul_f32_e32 v162, v164, v162
	v_mfma_f32_16x16x32_bf16 v[98:101], v[166:169], v[30:33], v[98:101]
	v_mul_f32_e32 v165, v121, v165
	v_mul_f32_e32 v182, 0xbfb8aa3b, v194
	v_exp_f32_e32 v182, v182
	v_mfma_f32_16x16x32_bf16 v[102:105], v[166:169], v[62:65], v[102:105]
	v_mul_f32_e32 v166, 0xbfb8aa3b, v192
	v_exp_f32_e32 v166, v166
	v_exp_f32_e32 v168, v165
	s_nop 0
	v_mul_f32_e32 v98, 0xbfb8aa3b, v98
	v_exp_f32_e32 v98, v98
	v_add_f32_e32 v164, 1.0, v166
	v_rcp_f32_e32 v166, v164
	v_mul_f32_e32 v164, 0xbfb8aa3b, v181
	v_exp_f32_e32 v169, v164
	v_fma_f32 v167, -v168, v168, 1.0 clamp
	s_nop 0
	v_sqrt_f32_e32 v167, v167
	v_add_f32_e32 v169, 1.0, v169
	v_mul_f32_e32 v164, v166, v228
	v_mul_f32_e32 v166, 0xbfb8aa3b, v193
	v_exp_f32_e32 v166, v166
	v_rcp_f32_e32 v169, v169
	v_mul_f32_e32 v164, v167, v164
	v_add_f32_e32 v98, 1.0, v98
	v_add_f32_e32 v166, 1.0, v166
	v_rcp_f32_e32 v180, v166
	v_mul_f32_e32 v169, v121, v169
	v_exp_f32_e32 v169, v169
	v_rcp_f32_e32 v98, v98
	v_mul_f32_e32 v102, 0xbfb8aa3b, v102
	v_mul_f32_e32 v166, v180, v230
	v_add_f32_e32 v180, 1.0, v182
	v_fma_f32 v181, -v169, v169, 1.0 clamp
	v_rcp_f32_e32 v180, v180
	v_mul_f32_e32 v182, 0xbfb8aa3b, v198
	v_sqrt_f32_e32 v181, v181
	v_exp_f32_e32 v182, v182
	v_mul_f32_e32 v180, v120, v180
	v_exp_f32_e32 v180, v180
	v_mul_f32_e32 v166, v181, v166
	v_add_f32_e32 v181, 1.0, v182
	v_rcp_f32_e32 v181, v181
	v_fma_f32 v185, -v180, v180, 1.0 clamp
	v_add_u32_e32 v182, 0x1000, v109
	v_sqrt_f32_e32 v185, v185
	ds_write2_b32 v182, v145, v180 offset1:16
	v_mul_f32_e32 v145, v181, v183
	v_mul_f32_e32 v183, 0xbfb8aa3b, v199
	v_exp_f32_e32 v183, v183
	v_add_f32_e32 v180, 1.0, v190
	v_mul_f32_e32 v145, v185, v145
	v_rcp_f32_e32 v180, v180
	v_add_u32_e32 v181, 0x2000, v109
	ds_write2_b32 v181, v179, v145 offset1:16
	v_add_f32_e32 v145, 1.0, v183
	v_mul_f32_e32 v179, 0xbfb8aa3b, v196
	v_rcp_f32_e32 v145, v145
	v_exp_f32_e32 v179, v179
	v_mul_f32_e32 v180, v120, v180
	v_exp_f32_e32 v180, v180
	v_mul_f32_e32 v145, v145, v227
	v_add_f32_e32 v163, 1.0, v179
	v_rcp_f32_e32 v163, v163
	ds_write2_b32 v182, v178, v180 offset0:64 offset1:80
	v_fma_f32 v178, -v180, v180, 1.0 clamp
	v_sqrt_f32_e32 v178, v178
	v_mul_f32_e32 v163, v120, v163
	v_exp_f32_e32 v163, v163
	v_mul_f32_e32 v98, v122, v98
	v_mul_f32_e32 v145, v178, v145
	v_mul_f32_e32 v178, 0xbfb8aa3b, v200
	v_exp_f32_e32 v178, v178
	ds_write2_b32 v181, v162, v145 offset0:64 offset1:80
	ds_write2_b32 v182, v168, v163 offset0:128 offset1:144
	v_fma_f32 v162, -v163, v163, 1.0 clamp
	v_mul_f32_e32 v163, 0xbfb8aa3b, v197
	v_exp_f32_e32 v163, v163
	v_add_f32_e32 v145, 1.0, v178
	v_rcp_f32_e32 v145, v145
	v_add_f32_e32 v163, 1.0, v163
	v_sqrt_f32_e32 v162, v162
	v_rcp_f32_e32 v163, v163
	v_mul_f32_e32 v145, v145, v229
	v_exp_f32_e32 v102, v102
	v_mul_f32_e32 v145, v162, v145
	v_mul_f32_e32 v162, 0xbfb8aa3b, v201
	v_mul_f32_e32 v163, v120, v163
	v_exp_f32_e32 v162, v162
	v_exp_f32_e32 v163, v163
	ds_write2_b32 v181, v164, v145 offset0:128 offset1:144
	v_exp_f32_e32 v98, v98
	v_add_f32_e32 v145, 1.0, v162
	ds_write2_b32 v182, v169, v163 offset0:192 offset1:208
	v_fma_f32 v162, -v163, v163, 1.0 clamp
	v_mul_f32_e32 v163, 0xbfb8aa3b, v186
	v_rcp_f32_e32 v145, v145
	v_exp_f32_e32 v163, v163
	v_sqrt_f32_e32 v162, v162
	v_mul_f32_e32 v145, v145, v231
	v_add_f32_e32 v163, 1.0, v163
	v_rcp_f32_e32 v163, v163
	v_mul_f32_e32 v145, v162, v145
	v_mul_f32_e32 v162, 0xbfb8aa3b, v202
	v_exp_f32_e32 v162, v162
	v_mul_f32_e32 v163, v123, v163
	v_exp_f32_e32 v178, v163
	ds_write2_b32 v181, v166, v145 offset0:192 offset1:208
	v_add_f32_e32 v145, 1.0, v162
	v_mul_f32_e32 v162, 0xbfb8aa3b, v187
	v_mul_f32_e32 v99, 0xbfb8aa3b, v99
	v_exp_f32_e32 v165, v162
	v_exp_f32_e32 v99, v99
	v_add_f32_e32 v102, 1.0, v102
	ds_write2_b32 v182, v178, v98 offset0:32 offset1:48
	v_fma_f32 v98, -v98, v98, 1.0 clamp
	v_add_f32_e32 v165, 1.0, v165
	v_rcp_f32_e32 v102, v102
	v_add_f32_e32 v99, 1.0, v99
	v_rcp_f32_e32 v165, v165
	v_sqrt_f32_e32 v98, v98
	v_rcp_f32_e32 v99, v99
	v_fma_f32 v164, -v178, v178, 1.0 clamp
	v_rcp_f32_e32 v145, v145
	v_mul_f32_e32 v102, v102, v233
	v_sqrt_f32_e32 v164, v164
	v_mul_f32_e32 v165, v123, v165
	v_mul_f32_e32 v98, v98, v102
	v_mul_f32_e32 v102, 0xbfb8aa3b, v103
	v_mul_f32_e32 v99, v122, v99
	v_exp_f32_e32 v179, v165
	v_exp_f32_e32 v102, v102
	v_exp_f32_e32 v99, v99
	v_mul_f32_e32 v145, v145, v232
	v_mul_f32_e32 v162, 0xbfb8aa3b, v203
	v_mul_f32_e32 v145, v164, v145
	v_mul_f32_e32 v164, 0xbfb8aa3b, v188
	v_exp_f32_e32 v162, v162
	v_exp_f32_e32 v167, v164
	ds_write2_b32 v181, v145, v98 offset0:32 offset1:48
	v_add_f32_e32 v98, 1.0, v102
	ds_write2_b32 v182, v179, v99 offset0:96 offset1:112
	v_fma_f32 v99, -v99, v99, 1.0 clamp
	v_rcp_f32_e32 v98, v98
	v_sqrt_f32_e32 v99, v99
	v_add_f32_e32 v162, 1.0, v162
	v_fma_f32 v166, -v179, v179, 1.0 clamp
	v_rcp_f32_e32 v162, v162
	v_mul_f32_e32 v100, 0xbfb8aa3b, v100
	v_mul_f32_e32 v98, v98, v235
	v_sqrt_f32_e32 v166, v166
	v_exp_f32_e32 v100, v100
	v_mul_f32_e32 v98, v99, v98
	v_mul_f32_e32 v99, 0xbfb8aa3b, v104
	v_exp_f32_e32 v99, v99
	v_mul_f32_e32 v162, v162, v234
	v_add_f32_e32 v167, 1.0, v167
	v_mul_f32_e32 v162, v166, v162
	v_add_f32_e32 v100, 1.0, v100
	v_rcp_f32_e32 v167, v167
	v_mul_f32_e32 v164, 0xbfb8aa3b, v204
	v_mul_f32_e32 v166, 0xbfb8aa3b, v189
	v_rcp_f32_e32 v100, v100
	ds_write2_b32 v181, v162, v98 offset0:96 offset1:112
	v_add_f32_e32 v98, 1.0, v99
	v_mul_f32_e32 v99, 0xbfb8aa3b, v101
	v_exp_f32_e32 v164, v164
	v_exp_f32_e32 v169, v166
	v_exp_f32_e32 v99, v99
	v_mul_f32_e32 v167, v123, v167
	v_mul_f32_e32 v100, v122, v100
	v_exp_f32_e32 v180, v167
	v_add_f32_e32 v164, 1.0, v164
	v_add_f32_e32 v169, 1.0, v169
	v_exp_f32_e32 v100, v100
	v_add_f32_e32 v99, 1.0, v99
	v_rcp_f32_e32 v164, v164
	v_rcp_f32_e32 v169, v169
	v_rcp_f32_e32 v99, v99
	v_fma_f32 v168, -v180, v180, 1.0 clamp
	ds_write2_b32 v182, v180, v100 offset0:160 offset1:176
	v_fma_f32 v100, -v100, v100, 1.0 clamp
	v_mul_f32_e32 v164, v164, v236
	v_mul_f32_e32 v166, 0xbfb8aa3b, v205
	v_mul_f32_e32 v169, v123, v169
	v_rcp_f32_e32 v98, v98
	v_mul_f32_e32 v101, 0xbfb8aa3b, v105
	v_mul_f32_e32 v99, v122, v99
	v_sqrt_f32_e32 v168, v168
	v_exp_f32_e32 v166, v166
	v_exp_f32_e32 v183, v169
	v_sqrt_f32_e32 v100, v100
	v_exp_f32_e32 v101, v101
	v_exp_f32_e32 v99, v99
	v_mul_f32_e32 v98, v98, v237
	v_mul_f32_e32 v164, v168, v164
	v_add_f32_e32 v166, 1.0, v166
	v_fma_f32 v185, -v183, v183, 1.0 clamp
	v_mul_f32_e32 v98, v100, v98
	v_add_f32_e32 v100, 1.0, v101
	v_fma_f32 v101, -v99, v99, 1.0 clamp
	v_rcp_f32_e32 v166, v166
	v_rcp_f32_e32 v100, v100
	v_sqrt_f32_e32 v185, v185
	v_sqrt_f32_e32 v101, v101
	v_mul_f32_e32 v166, v166, v238
	ds_write2_b32 v181, v164, v98 offset0:160 offset1:176
	ds_write2_b32 v182, v183, v99 offset0:224 offset1:240
	v_mul_f32_e32 v98, v100, v239
	v_mul_f32_e32 v166, v185, v166
	v_mul_f32_e32 v98, v101, v98
	ds_write2_b32 v181, v166, v98 offset0:224 offset1:240
	s_waitcnt lgkmcnt(0)
	ds_read2st64_b32 v[98:99], v1 offset0:32 offset1:33
	ds_read2st64_b32 v[100:101], v1 offset0:16 offset1:17
	ds_read2st64_b32 v[102:103], v1 offset0:18 offset1:19
	ds_read2st64_b32 v[104:105], v1 offset0:20 offset1:21
	ds_read2st64_b32 v[162:163], v1 offset0:22 offset1:23
	ds_read2st64_b32 v[164:165], v1 offset0:34 offset1:35
	ds_read2st64_b32 v[166:167], v1 offset0:36 offset1:37
	ds_read2st64_b32 v[168:169], v1 offset0:38 offset1:39
	ds_read2st64_b32 v[206:207], v1 offset0:40 offset1:41
	ds_read2st64_b32 v[208:209], v1 offset0:24 offset1:25
	ds_read2st64_b32 v[210:211], v1 offset0:26 offset1:27
	ds_read2st64_b32 v[212:213], v1 offset0:28 offset1:29
	ds_read2st64_b32 v[214:215], v1 offset0:30 offset1:31
	ds_read2st64_b32 v[216:217], v1 offset0:42 offset1:43
	ds_read2st64_b32 v[218:219], v1 offset0:44 offset1:45
	ds_read2st64_b32 v[220:221], v1 offset0:46 offset1:47
	s_waitcnt lgkmcnt(14)
	v_fma_f32 v98, 0, v100, v98
	v_fmac_f32_e32 v99, v98, v101
	v_mul_f32_e32 v101, v100, v101
	s_waitcnt lgkmcnt(10)
	v_fma_f32 v98, v99, v102, v164
	v_fmac_f32_e32 v165, v98, v103
	v_mul_f32_e32 v101, v101, v102
	v_mul_f32_e32 v101, v101, v103
	s_waitcnt lgkmcnt(9)
	v_fma_f32 v98, v165, v104, v166
	v_fmac_f32_e32 v167, v98, v105
	v_mul_f32_e32 v101, v101, v104
	v_mul_f32_e32 v101, v101, v105
	s_waitcnt lgkmcnt(8)
	v_fma_f32 v98, v167, v162, v168
	v_fmac_f32_e32 v169, v98, v163
	v_mul_f32_e32 v101, v101, v162
	v_mul_f32_e32 v101, v101, v163
	s_waitcnt lgkmcnt(6)
	v_fmac_f32_e32 v206, v169, v208
	v_mul_f32_e32 v101, v101, v208
	v_fmac_f32_e32 v207, v206, v209
	v_mul_f32_e32 v101, v101, v209
	s_waitcnt lgkmcnt(2)
	v_fmac_f32_e32 v216, v207, v210
	v_mul_f32_e32 v101, v101, v210
	v_fmac_f32_e32 v217, v216, v211
	v_mul_f32_e32 v101, v101, v211
	s_waitcnt lgkmcnt(1)
	v_fmac_f32_e32 v218, v217, v212
	v_mul_f32_e32 v101, v101, v212
	v_fmac_f32_e32 v219, v218, v213
	v_mul_f32_e32 v101, v101, v213
	s_waitcnt lgkmcnt(0)
	v_fmac_f32_e32 v220, v219, v214
	v_mul_f32_e32 v101, v101, v214
	v_fmac_f32_e32 v221, v220, v215
	v_mul_f32_e32 v101, v101, v215
	v_mov_b32_e32 v98, v221
	s_branch .LBB0_934

.LBB0_934:
	s_and_b32 s54, s37, 0x400
	s_lshl_b32 s54, s54, 2
	s_add_i32 s54, s54, 0
	s_add_i32 s54, s54, 0x18000
	s_add_i32 s55, s54, s51
	v_lshlrev_b32_e32 v99, 2, v106
	v_add_u32_e32 v100, s55, v99
	ds_write2st64_b32 v100, v101, v98 offset1:1
	s_waitcnt lgkmcnt(0)
	v_add_u32_e32 v98, s54, v99
	s_waitcnt lgkmcnt(0)
	s_barrier
	ds_read2st64_b32 v[178:179], v1 offset0:32 offset1:33
	ds_read2st64_b32 v[180:181], v1 offset0:16 offset1:17
	ds_read2st64_b32 v[182:183], v1 offset0:18 offset1:19
	ds_read2st64_b32 v[186:187], v1 offset0:20 offset1:21
	ds_read2st64_b32 v[188:189], v1 offset0:22 offset1:23
	ds_read2st64_b32 v[190:191], v1 offset0:34 offset1:35
	ds_read2st64_b32 v[192:193], v1 offset0:36 offset1:37
	ds_read2st64_b32 v[194:195], v1 offset0:38 offset1:39
	ds_read2st64_b32 v[206:207], v1 offset0:40 offset1:41
	ds_read2st64_b32 v[208:209], v1 offset0:24 offset1:25
	ds_read2st64_b32 v[210:211], v1 offset0:26 offset1:27
	ds_read2st64_b32 v[212:213], v1 offset0:28 offset1:29
	ds_read2st64_b32 v[214:215], v1 offset0:30 offset1:31
	ds_read2st64_b32 v[216:217], v1 offset0:42 offset1:43
	ds_read2st64_b32 v[218:219], v1 offset0:44 offset1:45
	ds_read2st64_b32 v[220:221], v1 offset0:46 offset1:47
	ds_read2st64_b32 v[164:165], v98 offset1:1
	ds_read2st64_b32 v[168:169], v98 offset0:2 offset1:3
	ds_read2st64_b32 v[166:167], v98 offset0:4 offset1:5
	ds_read2st64_b32 v[162:163], v98 offset0:6 offset1:7
	ds_read2st64_b32 v[104:105], v98 offset0:8 offset1:9
	ds_read2st64_b32 v[102:103], v98 offset0:10 offset1:11
	ds_read2st64_b32 v[100:101], v98 offset0:12 offset1:13
	ds_read2st64_b32 v[98:99], v98 offset0:14 offset1:15
	s_andn2_b64 vcc, exec, s[26:27]
	s_cbranch_vccnz .Lp6_zwait_last
	s_waitcnt vmcnt(19)
	s_branch .Lp6_zwait_done

.Lp6_zwait_done:
	s_andn2_b64 vcc, exec, s[28:29]
	s_waitcnt lgkmcnt(7)
	v_fmac_f32_e32 v165, v177, v164
	s_cbranch_vccnz .LBB0_937
	v_cndmask_b32_e64 v145, v165, v177, s[4:5]
	s_waitcnt lgkmcnt(6)
	v_fma_f32 v164, v168, v145, v169
	v_cndmask_b32_e64 v145, v145, v164, s[18:19]
	s_waitcnt lgkmcnt(5)
	v_fma_f32 v164, v166, v145, v167
	v_cndmask_b32_e64 v145, v145, v164, s[16:17]
	s_waitcnt lgkmcnt(4)
	v_fma_f32 v164, v162, v145, v163
	v_cndmask_b32_e64 v145, v145, v164, s[14:15]
	s_waitcnt lgkmcnt(3)
	v_fma_f32 v164, v104, v145, v105
	v_cndmask_b32_e64 v145, v145, v164, s[12:13]
	s_waitcnt lgkmcnt(2)
	v_fma_f32 v164, v102, v145, v103
	v_cndmask_b32_e64 v145, v145, v164, s[10:11]
	s_waitcnt lgkmcnt(1)
	v_fma_f32 v164, v100, v145, v101
	v_cndmask_b32_e64 v145, v145, v164, s[8:9]
	s_waitcnt lgkmcnt(0)
	v_fma_f32 v164, v98, v145, v99
	v_cndmask_b32_e64 v145, v145, v164, s[6:7]
	v_add_co_u32_e32 v196, vcc, s77, v158
	s_nop 1
	v_addc_co_u32_e32 v197, vcc, -1, v159, vcc
	v_fma_f32 v145, v145, v180, v178
	v_fmac_f32_e32 v179, v145, v181
	v_mul_f32_e32 v222, v125, v145
	v_mul_f32_e32 v223, v124, v179
	v_cvt_pk_bf16_f32 v222, v222, v223
	global_store_short v[196:197], v222, off offset:-1920
	global_store_short_d16_hi v[196:197], v222, off offset:-1792
	v_fma_f32 v145, v179, v182, v190
	v_fmac_f32_e32 v191, v145, v183
	v_mul_f32_e32 v224, v127, v145
	v_mul_f32_e32 v225, v126, v191
	v_cvt_pk_bf16_f32 v224, v224, v225
	global_store_short v[196:197], v224, off offset:-1664
	global_store_short_d16_hi v[196:197], v224, off offset:-1536
	v_fma_f32 v145, v191, v186, v192
	v_fmac_f32_e32 v193, v145, v187
	v_mul_f32_e32 v222, v131, v145
	v_mul_f32_e32 v223, v130, v193
	v_cvt_pk_bf16_f32 v222, v222, v223
	global_store_short v[196:197], v222, off offset:-1408
	global_store_short_d16_hi v[196:197], v222, off offset:-1280
	v_fma_f32 v145, v193, v188, v194
	v_fmac_f32_e32 v195, v145, v189
	v_mul_f32_e32 v224, v135, v145
	v_mul_f32_e32 v225, v134, v195
	v_cvt_pk_bf16_f32 v224, v224, v225
	global_store_short v[196:197], v224, off offset:-1152
	global_store_short_d16_hi v[196:197], v224, off offset:-1024
	v_fma_f32 v145, v195, v208, v206
	v_fmac_f32_e32 v207, v145, v209
	v_mul_f32_e32 v222, v139, v145
	v_mul_f32_e32 v223, v138, v207
	v_cvt_pk_bf16_f32 v222, v222, v223
	global_store_short v[196:197], v222, off offset:-896
	global_store_short_d16_hi v[196:197], v222, off offset:-768
	v_fma_f32 v145, v207, v210, v216
	v_fmac_f32_e32 v217, v145, v211
	v_mul_f32_e32 v224, v143, v145
	v_mul_f32_e32 v225, v142, v217
	v_cvt_pk_bf16_f32 v224, v224, v225
	global_store_short v[196:197], v224, off offset:-640
	global_store_short_d16_hi v[196:197], v224, off offset:-512
	v_fma_f32 v145, v217, v212, v218
	v_fmac_f32_e32 v219, v145, v213
	v_mul_f32_e32 v222, v149, v145
	v_mul_f32_e32 v223, v148, v219
	v_cvt_pk_bf16_f32 v222, v222, v223
	global_store_short v[196:197], v222, off offset:-384
	global_store_short_d16_hi v[196:197], v222, off offset:-256
	v_fma_f32 v145, v219, v214, v220
	v_fmac_f32_e32 v221, v145, v215
	v_mul_f32_e32 v224, v153, v145
	v_mul_f32_e32 v225, v152, v221
	v_cvt_pk_bf16_f32 v224, v224, v225
	global_store_short v[196:197], v224, off offset:-128
	global_store_short_d16_hi v[196:197], v224, off
	s_andn2_b64 vcc, exec, s[26:27]
	s_cbranch_vccnz .LBB0_937
	global_load_short_d16_hi v135, v[158:159], off offset:-1152 nt
	global_load_short_d16_hi v131, v[158:159], off offset:-1408 nt
	global_load_short_d16_hi v127, v[158:159], off offset:-1664 nt
	global_load_short_d16_hi v125, v[158:159], off offset:-1920 nt
	global_load_short_d16_hi v124, v[158:159], off offset:-1792 nt
	global_load_short_d16_hi v126, v[158:159], off offset:-1536 nt
	global_load_short_d16_hi v130, v[158:159], off offset:-1280 nt
	global_load_short_d16_hi v134, v[158:159], off offset:-1024 nt
	global_load_short_d16_hi v153, v[158:159], off offset:-128 nt
	global_load_short_d16_hi v149, v[158:159], off offset:-384 nt
	global_load_short_d16_hi v143, v[158:159], off offset:-640 nt
	global_load_short_d16_hi v139, v[158:159], off offset:-896 nt
	global_load_short_d16_hi v138, v[158:159], off offset:-768 nt
	global_load_short_d16_hi v142, v[158:159], off offset:-512 nt
	global_load_short_d16_hi v148, v[158:159], off offset:-256 nt
	global_load_short_d16_hi v152, v[158:159], off nt
